# v10 + phase A adaLN partial-sum job: all 32 weight-row loads issued up front with counted vmcnt (was 4 serialized batches)
# baseline (speedup 1.0000x reference)
.LBB0_19:
	s_mul_hi_i32 s4, s14, 0x2aaaaaab
	s_lshr_b32 s5, s4, 31
	s_ashr_i32 s15, s4, 2
	s_add_i32 s15, s15, s5
	s_lshl_b32 s4, s15, 8
	v_add_u32_e32 v0, s4, v20
	v_ashrrev_i32_e32 v1, 31, v0
	v_lshl_add_u64 v[0:1], v[0:1], 2, s[62:63]
	s_barrier
	global_load_dword v7, v[0:1], off
	s_mul_i32 s5, s15, 24
	v_add_u32_e32 v14, s4, v18
	s_sub_i32 s16, s14, s5
	v_mad_i64_i32 v[14:15], s[4:5], v14, s2, v[10:11]
	s_lshl_b32 s4, s16, 8
	s_ashr_i32 s5, s4, 31
	v_lshl_add_u64 v[14:15], s[4:5], 2, v[14:15]
	s_mov_b64 s[6:7], 0
	v_mov_b32_e32 v25, v22
	v_mov_b32_e32 v0, 0
	v_mov_b32_e32 v1, v9
	v_mov_b32_e32 v2, 0
	v_mov_b32_e32 v3, v9
	v_mov_b32_e32 v4, 0
	v_mov_b32_e32 v5, v9
	v_mov_b32_e32 v6, 0
	v_lshl_add_u64 v[14:15], v[14:15], 0, v[12:13]
	s_nop 0
	v_readfirstlane_b32 s98, v14
	v_readfirstlane_b32 s99, v15
	s_nop 4
	global_load_dwordx4 v[90:93], v12, s[98:99] nt
	s_add_u32 s98, s98, 0x30000
	s_addc_u32 s99, s99, 0
	global_load_dwordx4 v[94:97], v12, s[98:99] nt
	s_add_u32 s98, s98, 0x30000
	s_addc_u32 s99, s99, 0
	global_load_dwordx4 v[98:101], v12, s[98:99] nt
	s_add_u32 s98, s98, 0x30000
	s_addc_u32 s99, s99, 0
	global_load_dwordx4 v[102:105], v12, s[98:99] nt
	s_add_u32 s98, s98, 0x30000
	s_addc_u32 s99, s99, 0
	global_load_dwordx4 v[106:109], v12, s[98:99] nt
	s_add_u32 s98, s98, 0x30000
	s_addc_u32 s99, s99, 0
	global_load_dwordx4 v[110:113], v12, s[98:99] nt
	s_add_u32 s98, s98, 0x30000
	s_addc_u32 s99, s99, 0
	global_load_dwordx4 v[114:117], v12, s[98:99] nt
	s_add_u32 s98, s98, 0x30000
	s_addc_u32 s99, s99, 0
	global_load_dwordx4 v[118:121], v12, s[98:99] nt
	s_add_u32 s98, s98, 0x30000
	s_addc_u32 s99, s99, 0
	global_load_dwordx4 v[122:125], v12, s[98:99] nt
	s_add_u32 s98, s98, 0x30000
	s_addc_u32 s99, s99, 0
	global_load_dwordx4 v[126:129], v12, s[98:99] nt
	s_add_u32 s98, s98, 0x30000
	s_addc_u32 s99, s99, 0
	global_load_dwordx4 v[130:133], v12, s[98:99] nt
	s_add_u32 s98, s98, 0x30000
	s_addc_u32 s99, s99, 0
	global_load_dwordx4 v[134:137], v12, s[98:99] nt
	s_add_u32 s98, s98, 0x30000
	s_addc_u32 s99, s99, 0
	global_load_dwordx4 v[138:141], v12, s[98:99] nt
	s_add_u32 s98, s98, 0x30000
	s_addc_u32 s99, s99, 0
	global_load_dwordx4 v[142:145], v12, s[98:99] nt
	s_add_u32 s98, s98, 0x30000
	s_addc_u32 s99, s99, 0
	global_load_dwordx4 v[146:149], v12, s[98:99] nt
	s_add_u32 s98, s98, 0x30000
	s_addc_u32 s99, s99, 0
	global_load_dwordx4 v[150:153], v12, s[98:99] nt
	s_add_u32 s98, s98, 0x30000
	s_addc_u32 s99, s99, 0
	global_load_dwordx4 v[154:157], v12, s[98:99] nt
	s_add_u32 s98, s98, 0x30000
	s_addc_u32 s99, s99, 0
	global_load_dwordx4 v[158:161], v12, s[98:99] nt
	s_add_u32 s98, s98, 0x30000
	s_addc_u32 s99, s99, 0
	global_load_dwordx4 v[162:165], v12, s[98:99] nt
	s_add_u32 s98, s98, 0x30000
	s_addc_u32 s99, s99, 0
	global_load_dwordx4 v[166:169], v12, s[98:99] nt
	s_add_u32 s98, s98, 0x30000
	s_addc_u32 s99, s99, 0
	global_load_dwordx4 v[170:173], v12, s[98:99] nt
	s_add_u32 s98, s98, 0x30000
	s_addc_u32 s99, s99, 0
	global_load_dwordx4 v[174:177], v12, s[98:99] nt
	s_add_u32 s98, s98, 0x30000
	s_addc_u32 s99, s99, 0
	global_load_dwordx4 v[178:181], v12, s[98:99] nt
	s_add_u32 s98, s98, 0x30000
	s_addc_u32 s99, s99, 0
	global_load_dwordx4 v[216:219], v12, s[98:99] nt
	s_add_u32 s98, s98, 0x30000
	s_addc_u32 s99, s99, 0
	global_load_dwordx4 v[220:223], v12, s[98:99] nt
	s_add_u32 s98, s98, 0x30000
	s_addc_u32 s99, s99, 0
	global_load_dwordx4 v[224:227], v12, s[98:99] nt
	s_add_u32 s98, s98, 0x30000
	s_addc_u32 s99, s99, 0
	global_load_dwordx4 v[228:231], v12, s[98:99] nt
	s_add_u32 s98, s98, 0x30000
	s_addc_u32 s99, s99, 0
	global_load_dwordx4 v[232:235], v12, s[98:99] nt
	s_add_u32 s98, s98, 0x30000
	s_addc_u32 s99, s99, 0
	global_load_dwordx4 v[236:239], v12, s[98:99] nt
	s_add_u32 s98, s98, 0x30000
	s_addc_u32 s99, s99, 0
	global_load_dwordx4 v[240:243], v12, s[98:99] nt
	s_add_u32 s98, s98, 0x30000
	s_addc_u32 s99, s99, 0
	global_load_dwordx4 v[244:247], v12, s[98:99] nt
	s_add_u32 s98, s98, 0x30000
	s_addc_u32 s99, s99, 0
	global_load_dwordx4 v[248:251], v12, s[98:99] nt
	s_waitcnt vmcnt(32)
	ds_write_b32 v21, v7
	v_mov_b32_e32 v7, v9
	s_waitcnt lgkmcnt(0)
	s_barrier
	v_add_u32_e32 v72, 0x400, v25
	ds_read2_b32 v[26:27], v25 offset0:0 offset1:8
	ds_read2_b32 v[28:29], v25 offset0:16 offset1:24
	ds_read2_b32 v[30:31], v25 offset0:32 offset1:40
	ds_read2_b32 v[32:33], v25 offset0:48 offset1:56
	ds_read2_b32 v[184:185], v72 offset0:0 offset1:8
	ds_read2_b32 v[186:187], v72 offset0:16 offset1:24
	ds_read2_b32 v[188:189], v72 offset0:32 offset1:40
	ds_read2_b32 v[190:191], v72 offset0:48 offset1:56
	s_waitcnt lgkmcnt(0)
	ds_read2_b32 v[34:35], v25 offset0:64 offset1:72
	ds_read2_b32 v[36:37], v25 offset0:80 offset1:88
	ds_read2_b32 v[38:39], v25 offset0:96 offset1:104
	ds_read2_b32 v[40:41], v25 offset0:112 offset1:120
	ds_read2_b32 v[192:193], v72 offset0:64 offset1:72
	ds_read2_b32 v[194:195], v72 offset0:80 offset1:88
	ds_read2_b32 v[196:197], v72 offset0:96 offset1:104
	ds_read2_b32 v[198:199], v72 offset0:112 offset1:120
	s_waitcnt lgkmcnt(0)
	ds_read2_b32 v[42:43], v25 offset0:128 offset1:136
	ds_read2_b32 v[44:45], v25 offset0:144 offset1:152
	ds_read2_b32 v[46:47], v25 offset0:160 offset1:168
	ds_read2_b32 v[48:49], v25 offset0:176 offset1:184
	ds_read2_b32 v[200:201], v72 offset0:128 offset1:136
	ds_read2_b32 v[202:203], v72 offset0:144 offset1:152
	ds_read2_b32 v[204:205], v72 offset0:160 offset1:168
	ds_read2_b32 v[206:207], v72 offset0:176 offset1:184
	s_waitcnt lgkmcnt(0)
	ds_read2_b32 v[50:51], v25 offset0:192 offset1:200
	ds_read2_b32 v[52:53], v25 offset0:208 offset1:216
	ds_read2_b32 v[54:55], v25 offset0:224 offset1:232
	ds_read2_b32 v[56:57], v25 offset0:240 offset1:248
	ds_read2_b32 v[208:209], v72 offset0:192 offset1:200
	ds_read2_b32 v[210:211], v72 offset0:208 offset1:216
	ds_read2_b32 v[212:213], v72 offset0:224 offset1:232
	ds_read2_b32 v[214:215], v72 offset0:240 offset1:248
	s_waitcnt lgkmcnt(0)
	s_waitcnt vmcnt(31)
	v_pk_fma_f32 v[0:1], v[90:91], v[26:27], v[0:1] op_sel_hi:[1,0,1]
	v_pk_fma_f32 v[2:3], v[92:93], v[26:27], v[2:3] op_sel_hi:[1,0,1]
	v_pk_fma_f32 v[4:5], v[90:91], v[184:185], v[4:5] op_sel_hi:[1,0,1]
	v_pk_fma_f32 v[6:7], v[92:93], v[184:185], v[6:7] op_sel_hi:[1,0,1]
	s_waitcnt vmcnt(30)
	v_mov_b32_e32 v58, v27
	v_mov_b32_e32 v60, v185
	v_pk_fma_f32 v[0:1], v[94:95], v[58:59], v[0:1] op_sel_hi:[1,0,1]
	v_pk_fma_f32 v[2:3], v[96:97], v[58:59], v[2:3] op_sel_hi:[1,0,1]
	v_pk_fma_f32 v[4:5], v[94:95], v[60:61], v[4:5] op_sel_hi:[1,0,1]
	v_pk_fma_f32 v[6:7], v[96:97], v[60:61], v[6:7] op_sel_hi:[1,0,1]
	s_waitcnt vmcnt(29)
	v_pk_fma_f32 v[0:1], v[98:99], v[28:29], v[0:1] op_sel_hi:[1,0,1]
	v_pk_fma_f32 v[2:3], v[100:101], v[28:29], v[2:3] op_sel_hi:[1,0,1]
	v_pk_fma_f32 v[4:5], v[98:99], v[186:187], v[4:5] op_sel_hi:[1,0,1]
	v_pk_fma_f32 v[6:7], v[100:101], v[186:187], v[6:7] op_sel_hi:[1,0,1]
	s_waitcnt vmcnt(28)
	v_mov_b32_e32 v58, v29
	v_mov_b32_e32 v60, v187
	v_pk_fma_f32 v[0:1], v[102:103], v[58:59], v[0:1] op_sel_hi:[1,0,1]
	v_pk_fma_f32 v[2:3], v[104:105], v[58:59], v[2:3] op_sel_hi:[1,0,1]
	v_pk_fma_f32 v[4:5], v[102:103], v[60:61], v[4:5] op_sel_hi:[1,0,1]
	v_pk_fma_f32 v[6:7], v[104:105], v[60:61], v[6:7] op_sel_hi:[1,0,1]
	s_waitcnt vmcnt(27)
	v_pk_fma_f32 v[0:1], v[106:107], v[30:31], v[0:1] op_sel_hi:[1,0,1]
	v_pk_fma_f32 v[2:3], v[108:109], v[30:31], v[2:3] op_sel_hi:[1,0,1]
	v_pk_fma_f32 v[4:5], v[106:107], v[188:189], v[4:5] op_sel_hi:[1,0,1]
	v_pk_fma_f32 v[6:7], v[108:109], v[188:189], v[6:7] op_sel_hi:[1,0,1]
	s_waitcnt vmcnt(26)
	v_mov_b32_e32 v58, v31
	v_mov_b32_e32 v60, v189
	v_pk_fma_f32 v[0:1], v[110:111], v[58:59], v[0:1] op_sel_hi:[1,0,1]
	v_pk_fma_f32 v[2:3], v[112:113], v[58:59], v[2:3] op_sel_hi:[1,0,1]
	v_pk_fma_f32 v[4:5], v[110:111], v[60:61], v[4:5] op_sel_hi:[1,0,1]
	v_pk_fma_f32 v[6:7], v[112:113], v[60:61], v[6:7] op_sel_hi:[1,0,1]
	s_waitcnt vmcnt(25)
	v_pk_fma_f32 v[0:1], v[114:115], v[32:33], v[0:1] op_sel_hi:[1,0,1]
	v_pk_fma_f32 v[2:3], v[116:117], v[32:33], v[2:3] op_sel_hi:[1,0,1]
	v_pk_fma_f32 v[4:5], v[114:115], v[190:191], v[4:5] op_sel_hi:[1,0,1]
	v_pk_fma_f32 v[6:7], v[116:117], v[190:191], v[6:7] op_sel_hi:[1,0,1]
	s_waitcnt vmcnt(24)
	v_mov_b32_e32 v58, v33
	v_mov_b32_e32 v60, v191
	v_pk_fma_f32 v[0:1], v[118:119], v[58:59], v[0:1] op_sel_hi:[1,0,1]
	v_pk_fma_f32 v[2:3], v[120:121], v[58:59], v[2:3] op_sel_hi:[1,0,1]
	v_pk_fma_f32 v[4:5], v[118:119], v[60:61], v[4:5] op_sel_hi:[1,0,1]
	v_pk_fma_f32 v[6:7], v[120:121], v[60:61], v[6:7] op_sel_hi:[1,0,1]
	s_waitcnt vmcnt(23)
	v_pk_fma_f32 v[0:1], v[122:123], v[34:35], v[0:1] op_sel_hi:[1,0,1]
	v_pk_fma_f32 v[2:3], v[124:125], v[34:35], v[2:3] op_sel_hi:[1,0,1]
	v_pk_fma_f32 v[4:5], v[122:123], v[192:193], v[4:5] op_sel_hi:[1,0,1]
	v_pk_fma_f32 v[6:7], v[124:125], v[192:193], v[6:7] op_sel_hi:[1,0,1]
	s_waitcnt vmcnt(22)
	v_mov_b32_e32 v58, v35
	v_mov_b32_e32 v60, v193
	v_pk_fma_f32 v[0:1], v[126:127], v[58:59], v[0:1] op_sel_hi:[1,0,1]
	v_pk_fma_f32 v[2:3], v[128:129], v[58:59], v[2:3] op_sel_hi:[1,0,1]
	v_pk_fma_f32 v[4:5], v[126:127], v[60:61], v[4:5] op_sel_hi:[1,0,1]
	v_pk_fma_f32 v[6:7], v[128:129], v[60:61], v[6:7] op_sel_hi:[1,0,1]
	s_waitcnt vmcnt(21)
	v_pk_fma_f32 v[0:1], v[130:131], v[36:37], v[0:1] op_sel_hi:[1,0,1]
	v_pk_fma_f32 v[2:3], v[132:133], v[36:37], v[2:3] op_sel_hi:[1,0,1]
	v_pk_fma_f32 v[4:5], v[130:131], v[194:195], v[4:5] op_sel_hi:[1,0,1]
	v_pk_fma_f32 v[6:7], v[132:133], v[194:195], v[6:7] op_sel_hi:[1,0,1]
	s_waitcnt vmcnt(20)
	v_mov_b32_e32 v58, v37
	v_mov_b32_e32 v60, v195
	v_pk_fma_f32 v[0:1], v[134:135], v[58:59], v[0:1] op_sel_hi:[1,0,1]
	v_pk_fma_f32 v[2:3], v[136:137], v[58:59], v[2:3] op_sel_hi:[1,0,1]
	v_pk_fma_f32 v[4:5], v[134:135], v[60:61], v[4:5] op_sel_hi:[1,0,1]
	v_pk_fma_f32 v[6:7], v[136:137], v[60:61], v[6:7] op_sel_hi:[1,0,1]
	s_waitcnt vmcnt(19)
	v_pk_fma_f32 v[0:1], v[138:139], v[38:39], v[0:1] op_sel_hi:[1,0,1]
	v_pk_fma_f32 v[2:3], v[140:141], v[38:39], v[2:3] op_sel_hi:[1,0,1]
	v_pk_fma_f32 v[4:5], v[138:139], v[196:197], v[4:5] op_sel_hi:[1,0,1]
	v_pk_fma_f32 v[6:7], v[140:141], v[196:197], v[6:7] op_sel_hi:[1,0,1]
	s_waitcnt vmcnt(18)
	v_mov_b32_e32 v58, v39
	v_mov_b32_e32 v60, v197
	v_pk_fma_f32 v[0:1], v[142:143], v[58:59], v[0:1] op_sel_hi:[1,0,1]
	v_pk_fma_f32 v[2:3], v[144:145], v[58:59], v[2:3] op_sel_hi:[1,0,1]
	v_pk_fma_f32 v[4:5], v[142:143], v[60:61], v[4:5] op_sel_hi:[1,0,1]
	v_pk_fma_f32 v[6:7], v[144:145], v[60:61], v[6:7] op_sel_hi:[1,0,1]
	s_waitcnt vmcnt(17)
	v_pk_fma_f32 v[0:1], v[146:147], v[40:41], v[0:1] op_sel_hi:[1,0,1]
	v_pk_fma_f32 v[2:3], v[148:149], v[40:41], v[2:3] op_sel_hi:[1,0,1]
	v_pk_fma_f32 v[4:5], v[146:147], v[198:199], v[4:5] op_sel_hi:[1,0,1]
	v_pk_fma_f32 v[6:7], v[148:149], v[198:199], v[6:7] op_sel_hi:[1,0,1]
	s_waitcnt vmcnt(16)
	v_mov_b32_e32 v58, v41
	v_mov_b32_e32 v60, v199
	v_pk_fma_f32 v[0:1], v[150:151], v[58:59], v[0:1] op_sel_hi:[1,0,1]
	v_pk_fma_f32 v[2:3], v[152:153], v[58:59], v[2:3] op_sel_hi:[1,0,1]
	v_pk_fma_f32 v[4:5], v[150:151], v[60:61], v[4:5] op_sel_hi:[1,0,1]
	v_pk_fma_f32 v[6:7], v[152:153], v[60:61], v[6:7] op_sel_hi:[1,0,1]
	s_waitcnt vmcnt(15)
	v_pk_fma_f32 v[0:1], v[154:155], v[42:43], v[0:1] op_sel_hi:[1,0,1]
	v_pk_fma_f32 v[2:3], v[156:157], v[42:43], v[2:3] op_sel_hi:[1,0,1]
	v_pk_fma_f32 v[4:5], v[154:155], v[200:201], v[4:5] op_sel_hi:[1,0,1]
	v_pk_fma_f32 v[6:7], v[156:157], v[200:201], v[6:7] op_sel_hi:[1,0,1]
	s_waitcnt vmcnt(14)
	v_mov_b32_e32 v58, v43
	v_mov_b32_e32 v60, v201
	v_pk_fma_f32 v[0:1], v[158:159], v[58:59], v[0:1] op_sel_hi:[1,0,1]
	v_pk_fma_f32 v[2:3], v[160:161], v[58:59], v[2:3] op_sel_hi:[1,0,1]
	v_pk_fma_f32 v[4:5], v[158:159], v[60:61], v[4:5] op_sel_hi:[1,0,1]
	v_pk_fma_f32 v[6:7], v[160:161], v[60:61], v[6:7] op_sel_hi:[1,0,1]
	s_waitcnt vmcnt(13)
	v_pk_fma_f32 v[0:1], v[162:163], v[44:45], v[0:1] op_sel_hi:[1,0,1]
	v_pk_fma_f32 v[2:3], v[164:165], v[44:45], v[2:3] op_sel_hi:[1,0,1]
	v_pk_fma_f32 v[4:5], v[162:163], v[202:203], v[4:5] op_sel_hi:[1,0,1]
	v_pk_fma_f32 v[6:7], v[164:165], v[202:203], v[6:7] op_sel_hi:[1,0,1]
	s_waitcnt vmcnt(12)
	v_mov_b32_e32 v58, v45
	v_mov_b32_e32 v60, v203
	v_pk_fma_f32 v[0:1], v[166:167], v[58:59], v[0:1] op_sel_hi:[1,0,1]
	v_pk_fma_f32 v[2:3], v[168:169], v[58:59], v[2:3] op_sel_hi:[1,0,1]
	v_pk_fma_f32 v[4:5], v[166:167], v[60:61], v[4:5] op_sel_hi:[1,0,1]
	v_pk_fma_f32 v[6:7], v[168:169], v[60:61], v[6:7] op_sel_hi:[1,0,1]
	s_waitcnt vmcnt(11)
	v_pk_fma_f32 v[0:1], v[170:171], v[46:47], v[0:1] op_sel_hi:[1,0,1]
	v_pk_fma_f32 v[2:3], v[172:173], v[46:47], v[2:3] op_sel_hi:[1,0,1]
	v_pk_fma_f32 v[4:5], v[170:171], v[204:205], v[4:5] op_sel_hi:[1,0,1]
	v_pk_fma_f32 v[6:7], v[172:173], v[204:205], v[6:7] op_sel_hi:[1,0,1]
	s_waitcnt vmcnt(10)
	v_mov_b32_e32 v58, v47
	v_mov_b32_e32 v60, v205
	v_pk_fma_f32 v[0:1], v[174:175], v[58:59], v[0:1] op_sel_hi:[1,0,1]
	v_pk_fma_f32 v[2:3], v[176:177], v[58:59], v[2:3] op_sel_hi:[1,0,1]
	v_pk_fma_f32 v[4:5], v[174:175], v[60:61], v[4:5] op_sel_hi:[1,0,1]
	v_pk_fma_f32 v[6:7], v[176:177], v[60:61], v[6:7] op_sel_hi:[1,0,1]
	s_waitcnt vmcnt(9)
	v_pk_fma_f32 v[0:1], v[178:179], v[48:49], v[0:1] op_sel_hi:[1,0,1]
	v_pk_fma_f32 v[2:3], v[180:181], v[48:49], v[2:3] op_sel_hi:[1,0,1]
	v_pk_fma_f32 v[4:5], v[178:179], v[206:207], v[4:5] op_sel_hi:[1,0,1]
	v_pk_fma_f32 v[6:7], v[180:181], v[206:207], v[6:7] op_sel_hi:[1,0,1]
	s_waitcnt vmcnt(8)
	v_mov_b32_e32 v58, v49
	v_mov_b32_e32 v60, v207
	v_pk_fma_f32 v[0:1], v[216:217], v[58:59], v[0:1] op_sel_hi:[1,0,1]
	v_pk_fma_f32 v[2:3], v[218:219], v[58:59], v[2:3] op_sel_hi:[1,0,1]
	v_pk_fma_f32 v[4:5], v[216:217], v[60:61], v[4:5] op_sel_hi:[1,0,1]
	v_pk_fma_f32 v[6:7], v[218:219], v[60:61], v[6:7] op_sel_hi:[1,0,1]
	s_waitcnt vmcnt(7)
	v_pk_fma_f32 v[0:1], v[220:221], v[50:51], v[0:1] op_sel_hi:[1,0,1]
	v_pk_fma_f32 v[2:3], v[222:223], v[50:51], v[2:3] op_sel_hi:[1,0,1]
	v_pk_fma_f32 v[4:5], v[220:221], v[208:209], v[4:5] op_sel_hi:[1,0,1]
	v_pk_fma_f32 v[6:7], v[222:223], v[208:209], v[6:7] op_sel_hi:[1,0,1]
	s_waitcnt vmcnt(6)
	v_mov_b32_e32 v58, v51
	v_mov_b32_e32 v60, v209
	v_pk_fma_f32 v[0:1], v[224:225], v[58:59], v[0:1] op_sel_hi:[1,0,1]
	v_pk_fma_f32 v[2:3], v[226:227], v[58:59], v[2:3] op_sel_hi:[1,0,1]
	v_pk_fma_f32 v[4:5], v[224:225], v[60:61], v[4:5] op_sel_hi:[1,0,1]
	v_pk_fma_f32 v[6:7], v[226:227], v[60:61], v[6:7] op_sel_hi:[1,0,1]
	s_waitcnt vmcnt(5)
	v_pk_fma_f32 v[0:1], v[228:229], v[52:53], v[0:1] op_sel_hi:[1,0,1]
	v_pk_fma_f32 v[2:3], v[230:231], v[52:53], v[2:3] op_sel_hi:[1,0,1]
	v_pk_fma_f32 v[4:5], v[228:229], v[210:211], v[4:5] op_sel_hi:[1,0,1]
	v_pk_fma_f32 v[6:7], v[230:231], v[210:211], v[6:7] op_sel_hi:[1,0,1]
	s_waitcnt vmcnt(4)
	v_mov_b32_e32 v58, v53
	v_mov_b32_e32 v60, v211
	v_pk_fma_f32 v[0:1], v[232:233], v[58:59], v[0:1] op_sel_hi:[1,0,1]
	v_pk_fma_f32 v[2:3], v[234:235], v[58:59], v[2:3] op_sel_hi:[1,0,1]
	v_pk_fma_f32 v[4:5], v[232:233], v[60:61], v[4:5] op_sel_hi:[1,0,1]
	v_pk_fma_f32 v[6:7], v[234:235], v[60:61], v[6:7] op_sel_hi:[1,0,1]
	s_waitcnt vmcnt(3)
	v_pk_fma_f32 v[0:1], v[236:237], v[54:55], v[0:1] op_sel_hi:[1,0,1]
	v_pk_fma_f32 v[2:3], v[238:239], v[54:55], v[2:3] op_sel_hi:[1,0,1]
	v_pk_fma_f32 v[4:5], v[236:237], v[212:213], v[4:5] op_sel_hi:[1,0,1]
	v_pk_fma_f32 v[6:7], v[238:239], v[212:213], v[6:7] op_sel_hi:[1,0,1]
	s_waitcnt vmcnt(2)
	v_mov_b32_e32 v58, v55
	v_mov_b32_e32 v60, v213
	v_pk_fma_f32 v[0:1], v[240:241], v[58:59], v[0:1] op_sel_hi:[1,0,1]
	v_pk_fma_f32 v[2:3], v[242:243], v[58:59], v[2:3] op_sel_hi:[1,0,1]
	v_pk_fma_f32 v[4:5], v[240:241], v[60:61], v[4:5] op_sel_hi:[1,0,1]
	v_pk_fma_f32 v[6:7], v[242:243], v[60:61], v[6:7] op_sel_hi:[1,0,1]
	s_waitcnt vmcnt(1)
	v_pk_fma_f32 v[0:1], v[244:245], v[56:57], v[0:1] op_sel_hi:[1,0,1]
	v_pk_fma_f32 v[2:3], v[246:247], v[56:57], v[2:3] op_sel_hi:[1,0,1]
	v_pk_fma_f32 v[4:5], v[244:245], v[214:215], v[4:5] op_sel_hi:[1,0,1]
	v_pk_fma_f32 v[6:7], v[246:247], v[214:215], v[6:7] op_sel_hi:[1,0,1]
	s_waitcnt vmcnt(0)
	v_mov_b32_e32 v58, v57
	v_mov_b32_e32 v60, v215
	v_pk_fma_f32 v[0:1], v[248:249], v[58:59], v[0:1] op_sel_hi:[1,0,1]
	v_pk_fma_f32 v[2:3], v[250:251], v[58:59], v[2:3] op_sel_hi:[1,0,1]
	v_pk_fma_f32 v[4:5], v[248:249], v[60:61], v[4:5] op_sel_hi:[1,0,1]
	v_pk_fma_f32 v[6:7], v[250:251], v[60:61], v[6:7] op_sel_hi:[1,0,1]
	ds_write_b128 v23, v[0:3] offset:2048
	ds_write_b128 v23, v[4:7] offset:3072
	s_waitcnt lgkmcnt(0)
	s_barrier
	ds_read2st64_b32 v[0:1], v24 offset0:8 offset1:16
	ds_read2st64_b32 v[2:3], v24 offset0:24 offset1:32
	ds_read2st64_b32 v[4:5], v24 offset0:40 offset1:48
	s_add_i32 s14, s14, s96
	s_cmpk_gt_i32 s14, 0xbf
	s_waitcnt lgkmcnt(2)
	v_add_f32_e32 v0, 0, v0
	v_add_f32_e32 v6, v0, v1
	ds_read2st64_b32 v[0:1], v24 offset0:56 offset1:64
	s_waitcnt lgkmcnt(2)
	v_add_f32_e32 v2, v6, v2
	v_add_f32_e32 v2, v2, v3
	s_waitcnt lgkmcnt(1)
	v_add_f32_e32 v2, v2, v4
	v_add_f32_e32 v2, v2, v5
	s_waitcnt lgkmcnt(0)
	v_add_f32_e32 v0, v2, v0
	v_add_f32_e32 v2, v0, v1
	v_lshl_add_u32 v3, s15, 1, v19
	v_mov_b64_e32 v[0:1], s[0:1]
	v_mad_i64_i32 v[0:1], s[6:7], v3, s2, v[0:1]
	v_lshl_add_u64 v[0:1], s[4:5], 2, v[0:1]
	v_lshl_add_u64 v[0:1], v[0:1], 0, v[8:9]
	global_store_dword v[0:1], v2, off
	s_cbranch_scc0 .LBB0_19

	.amdhsa_kernel _Z4mega6Params
		.amdhsa_group_segment_fixed_size 0
		.amdhsa_private_segment_fixed_size 0
		.amdhsa_kernarg_size 384
		.amdhsa_user_sgpr_count 2
		.amdhsa_user_sgpr_dispatch_ptr 0
		.amdhsa_user_sgpr_queue_ptr 0
		.amdhsa_user_sgpr_kernarg_segment_ptr 1
		.amdhsa_user_sgpr_dispatch_id 0
		.amdhsa_user_sgpr_kernarg_preload_length 0
		.amdhsa_user_sgpr_kernarg_preload_offset 0
		.amdhsa_user_sgpr_private_segment_size 0
		.amdhsa_uses_dynamic_stack 0
		.amdhsa_enable_private_segment 0
		.amdhsa_system_sgpr_workgroup_id_x 1
		.amdhsa_system_sgpr_workgroup_id_y 0
		.amdhsa_system_sgpr_workgroup_id_z 0
		.amdhsa_system_sgpr_workgroup_info 0
		.amdhsa_system_vgpr_workitem_id 2
		.amdhsa_next_free_vgpr 253
		.amdhsa_next_free_sgpr 102
		.amdhsa_accum_offset 256
		.amdhsa_reserve_vcc 1
		.amdhsa_float_round_mode_32 0
		.amdhsa_float_round_mode_16_64 0
		.amdhsa_float_denorm_mode_32 3
		.amdhsa_float_denorm_mode_16_64 3
		.amdhsa_dx10_clamp 1
		.amdhsa_ieee_mode 1
		.amdhsa_fp16_overflow 0
		.amdhsa_tg_split 0
		.amdhsa_exception_fp_ieee_invalid_op 0
		.amdhsa_exception_fp_denorm_src 0
		.amdhsa_exception_fp_ieee_div_zero 0
		.amdhsa_exception_fp_ieee_overflow 0
		.amdhsa_exception_fp_ieee_underflow 0
		.amdhsa_exception_fp_ieee_inexact 0
		.amdhsa_exception_int_div_zero 0
	.end_amdhsa_kernel

amdhsa.kernels:
  - .agpr_count:     0
    .args:
      - .offset:         0
        .size:           128
        .value_kind:     by_value
      - .offset:         128
        .size:           4
        .value_kind:     hidden_block_count_x
      - .offset:         132
        .size:           4
        .value_kind:     hidden_block_count_y
      - .offset:         136
        .size:           4
        .value_kind:     hidden_block_count_z
      - .offset:         140
        .size:           2
        .value_kind:     hidden_group_size_x
      - .offset:         142
        .size:           2
        .value_kind:     hidden_group_size_y
      - .offset:         144
        .size:           2
        .value_kind:     hidden_group_size_z
      - .offset:         146
        .size:           2
        .value_kind:     hidden_remainder_x
      - .offset:         148
        .size:           2
        .value_kind:     hidden_remainder_y
      - .offset:         150
        .size:           2
        .value_kind:     hidden_remainder_z
      - .offset:         168
        .size:           8
        .value_kind:     hidden_global_offset_x
      - .offset:         176
        .size:           8
        .value_kind:     hidden_global_offset_y
      - .offset:         184
        .size:           8
        .value_kind:     hidden_global_offset_z
      - .offset:         192
        .size:           2
        .value_kind:     hidden_grid_dims
      - .offset:         216
        .size:           8
        .value_kind:     hidden_multigrid_sync_arg
      - .offset:         248
        .size:           4
        .value_kind:     hidden_dynamic_lds_size
    .group_segment_fixed_size: 0
    .kernarg_segment_align: 8
    .kernarg_segment_size: 384
    .language:       OpenCL C
    .language_version:
      - 2
      - 0
    .max_flat_workgroup_size: 512
    .name:           _Z4mega6Params
    .private_segment_fixed_size: 0
    .sgpr_count:     108
    .sgpr_spill_count: 43
    .symbol:         _Z4mega6Params.kd
    .uniform_work_group_size: 1
    .uses_dynamic_stack: false
    .vgpr_count:     253
    .vgpr_spill_count: 0
    .wavefront_size: 64
